# attnA combine epilogue: subln gain loads batched 8 deep instead of 16 serial load+store round trips
# speedup vs baseline: 1.0002x; 1.0002x over previous
; __device__ __forceinline__ float xhalf_sum(float m) { unsigned a = __builtin_bit_cast(unsigned, m), b = a; xswap(a, b); return __builtin_bit_cast(float, a) + __builtin_bit_cast(float, b); }
; __device__ __forceinline__ void attn_unit_a(FLAS unsigned char* lds, const Unit u) {
;     ...
;     if (NT & 1) { FA_PVP((NT - 1) & 3, pwb); } else { FA_PVP((NT - 1) & 3, pwa); }
;     ...
;     const float inv = 1.0f / xhalf_sum(lsum);
;     bf16_t* op = u.O + (size_t)(u.tok0 + q) * u.ldo + 4 * hi;
;     if (u.comb) {
;         const float lam = *u.lamp, gsc = 1.0f - u.lam_init;
;         const bf16_t* o1p = u.O1 + (size_t)(u.tok0 + q) * 512 + 4 * hi;
;         float ss = 0.f;
; #pragma unroll
;         for (int db = 0; db < NDB; ++db)
; #pragma unroll
;             for (int g = 0; g < 4; ++g) {
;                 const unsigned long long w = __hip_atomic_load((const unsigned long long*)(o1p + db * 32 + 8 * g), __ATOMIC_RELAXED, __HIP_MEMORY_SCOPE_AGENT);
.LBB0_479:
	v_cvt_pk_bf16_f32 v196, v72, v73
	v_cvt_pk_bf16_f32 v197, v74, v75
	v_cvt_pk_bf16_f32 v198, v76, v77
	v_cvt_pk_bf16_f32 v199, v78, v79
	v_cvt_pk_bf16_f32 v192, v80, v81
	v_cvt_pk_bf16_f32 v193, v82, v83
	v_cvt_pk_bf16_f32 v194, v84, v85
	v_cvt_pk_bf16_f32 v195, v86, v87
	v_cvt_pk_bf16_f32 v188, v88, v89
	v_cvt_pk_bf16_f32 v189, v90, v91
	v_cvt_pk_bf16_f32 v190, v92, v93
	v_cvt_pk_bf16_f32 v191, v94, v95
	v_readlane_b32 s12, v254, 48
	s_lshl_b32 s0, s26, 1
	s_add_u32 s0, s16, s0
	v_add3_u32 v82, s12, v246, v224
	ds_read_b128 v[64:67], v82
	ds_read_b128 v[68:71], v82 offset:4608
	ds_read_b128 v[72:75], v82 offset:9216
	ds_read_b128 v[76:79], v82 offset:13824
	s_addc_u32 s1, s17, 0
	s_cmp_eq_u32 s44, 0
	v_mov_b32_e32 v240, v213
	s_cselect_b32 s4, s0, s45
	s_cselect_b32 s5, s1, s46
	s_movk_i32 s12, 0x200
	s_cselect_b32 s12, s12, 0x600
	s_cmp_lg_u32 s44, 0
	v_mov_b32_e32 v80, s4
	v_mov_b32_e32 v81, s5
	s_waitcnt lgkmcnt(3)
	v_mfma_f32_32x32x16_bf16 v[48:63], v[64:67], v[204:207], v[48:63]
	ds_read_b128 v[64:67], v82 offset:32
	s_waitcnt lgkmcnt(3)
	v_mfma_f32_32x32x16_bf16 v[32:47], v[68:71], v[204:207], v[32:47]
	ds_read_b128 v[68:71], v82 offset:4640
	s_waitcnt lgkmcnt(3)
	v_mfma_f32_32x32x16_bf16 v[16:31], v[72:75], v[204:207], v[16:31]
	ds_read_b128 v[72:75], v82 offset:9248
	s_waitcnt lgkmcnt(3)
	v_mfma_f32_32x32x16_bf16 v[0:15], v[76:79], v[204:207], v[0:15]
	ds_read_b128 v[76:79], v82 offset:13856
	s_waitcnt lgkmcnt(3)
	v_mfma_f32_32x32x16_bf16 v[48:63], v[64:67], v[196:199], v[48:63]
	ds_read_b128 v[64:67], v82 offset:64
	s_waitcnt lgkmcnt(3)
	v_mfma_f32_32x32x16_bf16 v[32:47], v[68:71], v[196:199], v[32:47]
	ds_read_b128 v[68:71], v82 offset:4672
	s_waitcnt lgkmcnt(3)
	v_mfma_f32_32x32x16_bf16 v[16:31], v[72:75], v[196:199], v[16:31]
	ds_read_b128 v[72:75], v82 offset:9280
	s_waitcnt lgkmcnt(3)
	v_mfma_f32_32x32x16_bf16 v[0:15], v[76:79], v[196:199], v[0:15]
	ds_read_b128 v[76:79], v82 offset:13888
	s_waitcnt lgkmcnt(3)
	v_mfma_f32_32x32x16_bf16 v[48:63], v[64:67], v[192:195], v[48:63]
	ds_read_b128 v[64:67], v82 offset:96
	s_waitcnt lgkmcnt(3)
	v_mfma_f32_32x32x16_bf16 v[32:47], v[68:71], v[192:195], v[32:47]
	ds_read_b128 v[68:71], v82 offset:4704
	s_waitcnt lgkmcnt(3)
	v_mfma_f32_32x32x16_bf16 v[16:31], v[72:75], v[192:195], v[16:31]
	ds_read_b128 v[72:75], v82 offset:9312
	s_waitcnt lgkmcnt(3)
	v_mfma_f32_32x32x16_bf16 v[0:15], v[76:79], v[192:195], v[0:15]
	ds_read_b128 v[76:79], v82 offset:13920
	s_waitcnt lgkmcnt(3)
	v_mfma_f32_32x32x16_bf16 v[48:63], v[64:67], v[188:191], v[48:63]
	s_waitcnt lgkmcnt(2)
	v_mfma_f32_32x32x16_bf16 v[32:47], v[68:71], v[188:191], v[32:47]
	s_waitcnt lgkmcnt(1)
	v_mfma_f32_32x32x16_bf16 v[16:31], v[72:75], v[188:191], v[16:31]
	s_waitcnt lgkmcnt(0)
	v_mfma_f32_32x32x16_bf16 v[0:15], v[76:79], v[188:191], v[0:15]
	v_mov_b32_e32 v64, v212
	s_nop 1
	v_permlane32_swap_b32 v212, v64
	s_nop 1
	v_lshlrev_b32_e32 v208, 3, v243
	v_add_f32_e32 v64, v212, v64
	v_div_scale_f32 v65, s[4:5], v64, v64, 1.0
	v_rcp_f32_e32 v66, v65
	v_div_scale_f32 v67, vcc, 1.0, v64, 1.0
	v_mov_b32_e32 v244, v227
	v_fma_f32 v68, -v65, v66, 1.0
	v_fmac_f32_e32 v66, v68, v66
	v_mul_f32_e32 v68, v67, v66
	v_fma_f32 v69, -v65, v68, v67
	v_fmac_f32_e32 v68, v69, v66
	v_fma_f32 v65, -v65, v68, v67
	v_div_fmas_f32 v65, v65, v66, v68
	v_div_fixup_f32 v66, v65, v64, 1.0
	v_mad_i64_i32 v[64:65], s[4:5], s12, v222, 0
	v_lshl_add_u64 v[64:65], v[64:65], 1, v[80:81]
	v_lshl_add_u64 v[64:65], v[64:65], 0, v[208:209]
	s_mov_b64 s[4:5], -1
	s_cbranch_scc0 .LBB0_481
	v_lshlrev_b32_e32 v67, 2, v243
	v_lshlrev_b64 v[68:69], 10, v[222:223]
	v_lshl_add_u64 v[68:69], s[0:1], 0, v[68:69]
	v_lshlrev_b32_e32 v208, 1, v67
	v_lshl_add_u64 v[68:69], v[68:69], 0, v[208:209]
	global_load_dword v70, v209, s[6:7]
	global_load_dwordx2 v[72:73], v[68:69], off sc1
	global_load_dwordx2 v[74:75], v[68:69], off offset:16 sc1
	global_load_dwordx2 v[76:77], v[68:69], off offset:32 sc1
	global_load_dwordx2 v[78:79], v[68:69], off offset:48 sc1
	global_load_dwordx2 v[80:81], v[68:69], off offset:64 sc1
	global_load_dwordx2 v[82:83], v[68:69], off offset:80 sc1
	global_load_dwordx2 v[84:85], v[68:69], off offset:96 sc1
	global_load_dwordx2 v[86:87], v[68:69], off offset:112 sc1
	global_load_dwordx2 v[88:89], v[68:69], off offset:128 sc1
	global_load_dwordx2 v[90:91], v[68:69], off offset:144 sc1
	global_load_dwordx2 v[92:93], v[68:69], off offset:160 sc1
	global_load_dwordx2 v[94:95], v[68:69], off offset:176 sc1
	global_load_dwordx2 v[96:97], v[68:69], off offset:192 sc1
	global_load_dwordx2 v[98:99], v[68:69], off offset:208 sc1
	global_load_dwordx2 v[100:101], v[68:69], off offset:224 sc1
	s_nop 0
	global_load_dwordx2 v[68:69], v[68:69], off offset:240 sc1
	v_lshlrev_b32_e32 v67, 2, v67
	s_waitcnt vmcnt(15)
	v_lshlrev_b32_e32 v102, 16, v72
	v_and_b32_e32 v103, 0xffff0000, v72
	v_lshlrev_b32_e32 v72, 16, v73
	s_waitcnt vmcnt(12)
	v_lshlrev_b32_e32 v108, 16, v78
	v_and_b32_e32 v109, 0xffff0000, v78
	v_lshlrev_b32_e32 v110, 16, v79
	v_and_b32_e32 v111, 0xffff0000, v79
	v_pk_mul_f32 v[78:79], v[14:15], v[66:67] op_sel_hi:[1,0]
	v_and_b32_e32 v73, 0xffff0000, v73
	s_waitcnt vmcnt(9)
	v_lshlrev_b32_e32 v142, 16, v84
	v_and_b32_e32 v143, 0xffff0000, v84
	v_lshlrev_b32_e32 v144, 16, v85
	v_and_b32_e32 v145, 0xffff0000, v85
	v_lshlrev_b32_e32 v116, 16, v80
	v_and_b32_e32 v117, 0xffff0000, v80
	s_waitcnt vmcnt(0)
; __device__ __forceinline__ void attn_unit_a(FLAS unsigned char* lds, const Unit u) {
;     ...
;             for (int g = 0; g < 4; ++g) {
;                 const unsigned long long w = __hip_atomic_load((const unsigned long long*)(o1p + db * 32 + 8 * g), __ATOMIC_RELAXED, __HIP_MEMORY_SCOPE_AGENT);
;                 const unsigned w0 = (unsigned)w, w1 = (unsigned)(w >> 32);
;                 const float a0 = __builtin_bit_cast(float, w0 << 16), a1 = __builtin_bit_cast(float, w0 & 0xffff0000u), a2 = __builtin_bit_cast(float, w1 << 16), a3 = __builtin_bit_cast(float, w1 & 0xffff0000u);
;                 const float x0 = a0 - lam * (o[db][4 * g] * inv), x1 = a1 - lam * (o[db][4 * g + 1] * inv), x2 = a2 - lam * (o[db][4 * g + 2] * inv), x3 = a3 - lam * (o[db][4 * g + 3] * inv);
;                 o[db][4 * g] = x0; o[db][4 * g + 1] = x1; o[db][4 * g + 2] = x2; o[db][4 * g + 3] = x3; ss += (x0 * x0 + x1 * x1) + (x2 * x2 + x3 * x3); }
	v_lshlrev_b32_e32 v114, 16, v68
	v_and_b32_e32 v115, 0xffff0000, v68
	v_lshlrev_b32_e32 v68, 16, v69
	v_and_b32_e32 v69, 0xffff0000, v69
	v_pk_fma_f32 v[68:69], v[78:79], v[70:71], v[68:69] op_sel_hi:[1,0,1] neg_lo:[1,0,0] neg_hi:[1,0,0]
	v_pk_mul_f32 v[78:79], v[50:51], v[66:67] op_sel_hi:[1,0]
	v_lshlrev_b32_e32 v104, 16, v74
	v_pk_fma_f32 v[72:73], v[78:79], v[70:71], v[72:73] op_sel_hi:[1,0,1] neg_lo:[1,0,0] neg_hi:[1,0,0]
	v_and_b32_e32 v105, 0xffff0000, v74
	v_mul_f32_e32 v78, v73, v73
	v_pk_fma_f32 v[84:85], v[72:73], v[72:73], v[78:79] op_sel_hi:[1,1,0]
	v_pk_mul_f32 v[78:79], v[48:49], v[66:67] op_sel_hi:[1,0]
	v_lshlrev_b32_e32 v74, 16, v75
	v_pk_fma_f32 v[78:79], v[78:79], v[70:71], v[102:103] op_sel_hi:[1,0,1] neg_lo:[1,0,0] neg_hi:[1,0,0]
	v_and_b32_e32 v75, 0xffff0000, v75
	v_mul_f32_e32 v80, v79, v79
	v_lshlrev_b32_e32 v136, 16, v81
	v_and_b32_e32 v137, 0xffff0000, v81
	v_lshlrev_b32_e32 v146, 16, v86
	v_and_b32_e32 v147, 0xffff0000, v86
	v_lshlrev_b32_e32 v148, 16, v87
	v_and_b32_e32 v149, 0xffff0000, v87
	v_pk_fma_f32 v[86:87], v[78:79], v[78:79], v[80:81] op_sel_hi:[1,1,0]
	v_pk_mul_f32 v[80:81], v[54:55], v[66:67] op_sel_hi:[1,0]
	v_lshlrev_b32_e32 v150, 16, v88
	v_pk_fma_f32 v[74:75], v[80:81], v[70:71], v[74:75] op_sel_hi:[1,0,1] neg_lo:[1,0,0] neg_hi:[1,0,0]
	v_and_b32_e32 v151, 0xffff0000, v88
	v_mul_f32_e32 v80, v75, v75
	v_lshlrev_b32_e32 v152, 16, v89
	v_and_b32_e32 v153, 0xffff0000, v89
	v_pk_fma_f32 v[88:89], v[74:75], v[74:75], v[80:81] op_sel_hi:[1,1,0]
	v_pk_mul_f32 v[80:81], v[52:53], v[66:67] op_sel_hi:[1,0]
	v_lshlrev_b32_e32 v138, 16, v82
	v_pk_fma_f32 v[80:81], v[80:81], v[70:71], v[104:105] op_sel_hi:[1,0,1] neg_lo:[1,0,0] neg_hi:[1,0,0]
	v_and_b32_e32 v139, 0xffff0000, v82
	v_mul_f32_e32 v82, v81, v81
	v_lshlrev_b32_e32 v106, 16, v76
	v_and_b32_e32 v107, 0xffff0000, v76
	v_lshlrev_b32_e32 v76, 16, v77
	v_and_b32_e32 v77, 0xffff0000, v77
	v_lshlrev_b32_e32 v140, 16, v83
	v_and_b32_e32 v141, 0xffff0000, v83
	v_lshlrev_b32_e32 v154, 16, v90
	v_and_b32_e32 v155, 0xffff0000, v90
	v_lshlrev_b32_e32 v156, 16, v91
	v_and_b32_e32 v157, 0xffff0000, v91
	v_pk_fma_f32 v[90:91], v[80:81], v[80:81], v[82:83] op_sel_hi:[1,1,0]
	v_pk_mul_f32 v[82:83], v[58:59], v[66:67] op_sel_hi:[1,0]
	v_lshlrev_b32_e32 v118, 16, v92
	v_pk_fma_f32 v[76:77], v[82:83], v[70:71], v[76:77] op_sel_hi:[1,0,1] neg_lo:[1,0,0] neg_hi:[1,0,0]
	v_pk_mul_f32 v[82:83], v[56:57], v[66:67] op_sel_hi:[1,0]
	v_and_b32_e32 v119, 0xffff0000, v92
	v_pk_fma_f32 v[82:83], v[82:83], v[70:71], v[106:107] op_sel_hi:[1,0,1] neg_lo:[1,0,0] neg_hi:[1,0,0]
	v_lshlrev_b32_e32 v158, 16, v93
	v_and_b32_e32 v159, 0xffff0000, v93
	v_lshlrev_b32_e32 v122, 16, v94
	v_and_b32_e32 v123, 0xffff0000, v94
	v_lshlrev_b32_e32 v112, 16, v95
	v_and_b32_e32 v113, 0xffff0000, v95
	v_pk_mul_f32 v[92:93], v[76:77], v[76:77]
	v_pk_mul_f32 v[94:95], v[82:83], v[82:83]
	v_mov_b32_e32 v91, v92
	v_mov_b32_e32 v89, v93
	v_mov_b32_e32 v87, v94
	v_mov_b32_e32 v85, v95
	v_pk_add_f32 v[88:89], v[90:91], v[88:89]
	v_pk_add_f32 v[84:85], v[86:87], v[84:85]
	v_lshlrev_b32_e32 v132, 16, v96
	v_pk_add_f32 v[84:85], v[84:85], v[88:89]
	v_and_b32_e32 v133, 0xffff0000, v96
	v_lshlrev_b32_e32 v124, 16, v97
	v_and_b32_e32 v125, 0xffff0000, v97
	v_pk_add_f32 v[96:97], v[84:85], v[84:85] op_sel:[0,1] op_sel_hi:[1,0]
	v_pk_mul_f32 v[84:85], v[62:63], v[66:67] op_sel_hi:[1,0]
	v_pk_mul_f32 v[86:87], v[60:61], v[66:67] op_sel_hi:[1,0]
	v_pk_fma_f32 v[84:85], v[84:85], v[70:71], v[110:111] op_sel_hi:[1,0,1] neg_lo:[1,0,0] neg_hi:[1,0,0]
	v_pk_fma_f32 v[90:91], v[86:87], v[70:71], v[108:109] op_sel_hi:[1,0,1] neg_lo:[1,0,0] neg_hi:[1,0,0]
	v_mov_b32_e32 v89, v85
	v_mov_b32_e32 v88, v91
	v_mov_b32_e32 v86, v90
	v_mov_b32_e32 v87, v84
	v_pk_mul_f32 v[88:89], v[88:89], v[88:89]
	v_lshlrev_b32_e32 v134, 16, v98
	v_pk_fma_f32 v[86:87], v[86:87], v[86:87], v[88:89]
	v_and_b32_e32 v135, 0xffff0000, v98
	v_lshlrev_b32_e32 v126, 16, v99
	v_and_b32_e32 v127, 0xffff0000, v99
	v_pk_add_f32 v[98:99], v[86:87], v[86:87] op_sel:[0,1] op_sel_hi:[1,0]
	v_pk_mul_f32 v[86:87], v[34:35], v[66:67] op_sel_hi:[1,0]
	v_lshlrev_b32_e32 v120, 16, v100
	v_pk_fma_f32 v[86:87], v[86:87], v[70:71], v[136:137] op_sel_hi:[1,0,1] neg_lo:[1,0,0] neg_hi:[1,0,0]
	v_and_b32_e32 v121, 0xffff0000, v100
	v_mul_f32_e32 v88, v87, v87
	v_lshlrev_b32_e32 v130, 16, v101
	v_and_b32_e32 v131, 0xffff0000, v101
	v_pk_fma_f32 v[100:101], v[86:87], v[86:87], v[88:89] op_sel_hi:[1,1,0]
	v_pk_mul_f32 v[88:89], v[32:33], v[66:67] op_sel_hi:[1,0]
	v_pk_mul_f32 v[94:95], v[36:37], v[66:67] op_sel_hi:[1,0]
	v_pk_fma_f32 v[92:93], v[88:89], v[70:71], v[116:117] op_sel_hi:[1,0,1] neg_lo:[1,0,0] neg_hi:[1,0,0]
	v_pk_fma_f32 v[94:95], v[94:95], v[70:71], v[138:139] op_sel_hi:[1,0,1] neg_lo:[1,0,0] neg_hi:[1,0,0]
	v_mul_f32_e32 v88, v93, v93
	v_pk_fma_f32 v[102:103], v[92:93], v[92:93], v[88:89] op_sel_hi:[1,1,0]
	v_pk_mul_f32 v[88:89], v[38:39], v[66:67] op_sel_hi:[1,0]
	v_pk_mul_f32 v[106:107], v[94:95], v[94:95]
	v_pk_fma_f32 v[88:89], v[88:89], v[70:71], v[140:141] op_sel_hi:[1,0,1] neg_lo:[1,0,0] neg_hi:[1,0,0]
	v_mov_b32_e32 v97, v106
	v_pk_mul_f32 v[104:105], v[88:89], v[88:89]
	v_mov_b32_e32 v99, v107
	v_mov_b32_e32 v103, v104
	v_mov_b32_e32 v101, v105
	v_pk_add_f32 v[100:101], v[102:103], v[100:101]
	v_pk_add_f32 v[96:97], v[96:97], v[98:99]
	v_pk_mul_f32 v[98:99], v[40:41], v[66:67] op_sel_hi:[1,0]
	v_pk_add_f32 v[96:97], v[96:97], v[100:101]
	v_pk_fma_f32 v[102:103], v[98:99], v[70:71], v[142:143] op_sel_hi:[1,0,1] neg_lo:[1,0,0] neg_hi:[1,0,0]
	v_pk_add_f32 v[108:109], v[96:97], v[96:97] op_sel:[0,1] op_sel_hi:[1,0]
	v_pk_mul_f32 v[96:97], v[42:43], v[66:67] op_sel_hi:[1,0]
; __device__ __forceinline__ float xhalf_sum(float m) { unsigned a = __builtin_bit_cast(unsigned, m), b = a; xswap(a, b); return __builtin_bit_cast(float, a) + __builtin_bit_cast(float, b); }
; __device__ __forceinline__ void attn_unit_a(FLAS unsigned char* lds, const Unit u) {
;     ...
;             for (int g = 0; g < 4; ++g) {
;                 const unsigned long long w = __hip_atomic_load((const unsigned long long*)(o1p + db * 32 + 8 * g), __ATOMIC_RELAXED, __HIP_MEMORY_SCOPE_AGENT);
;                 const unsigned w0 = (unsigned)w, w1 = (unsigned)(w >> 32);
;                 const float a0 = __builtin_bit_cast(float, w0 << 16), a1 = __builtin_bit_cast(float, w0 & 0xffff0000u), a2 = __builtin_bit_cast(float, w1 << 16), a3 = __builtin_bit_cast(float, w1 & 0xffff0000u);
;                 const float x0 = a0 - lam * (o[db][4 * g] * inv), x1 = a1 - lam * (o[db][4 * g + 1] * inv), x2 = a2 - lam * (o[db][4 * g + 2] * inv), x3 = a3 - lam * (o[db][4 * g + 3] * inv);
;                 o[db][4 * g] = x0; o[db][4 * g + 1] = x1; o[db][4 * g + 2] = x2; o[db][4 * g + 3] = x3; ss += (x0 * x0 + x1 * x1) + (x2 * x2 + x3 * x3); }
;         const float rr = 1.0f / sqrtf(xhalf_sum(ss) * (1.f / 128.f) + 1e-6f) * gsc;
	v_mov_b32_e32 v100, v103
	v_pk_fma_f32 v[96:97], v[96:97], v[70:71], v[144:145] op_sel_hi:[1,0,1] neg_lo:[1,0,0] neg_hi:[1,0,0]
	v_mov_b32_e32 v98, v102
	v_mov_b32_e32 v101, v97
	v_mov_b32_e32 v99, v96
	v_pk_mul_f32 v[100:101], v[100:101], v[100:101]
	v_pk_mul_f32 v[104:105], v[16:17], v[66:67] op_sel_hi:[1,0]
	v_pk_fma_f32 v[98:99], v[98:99], v[98:99], v[100:101]
	v_pk_fma_f32 v[104:105], v[104:105], v[70:71], v[150:151] op_sel_hi:[1,0,1] neg_lo:[1,0,0] neg_hi:[1,0,0]
	v_pk_add_f32 v[110:111], v[98:99], v[98:99] op_sel:[0,1] op_sel_hi:[1,0]
	v_pk_mul_f32 v[98:99], v[46:47], v[66:67] op_sel_hi:[1,0]
	v_pk_mul_f32 v[140:141], v[104:105], v[104:105]
	v_pk_fma_f32 v[98:99], v[98:99], v[70:71], v[148:149] op_sel_hi:[1,0,1] neg_lo:[1,0,0] neg_hi:[1,0,0]
	v_mov_b32_e32 v109, v140
	v_mul_f32_e32 v100, v99, v99
	v_pk_fma_f32 v[116:117], v[98:99], v[98:99], v[100:101] op_sel_hi:[1,1,0]
	v_pk_mul_f32 v[100:101], v[44:45], v[66:67] op_sel_hi:[1,0]
	v_mov_b32_e32 v111, v141
	v_pk_fma_f32 v[106:107], v[100:101], v[70:71], v[146:147] op_sel_hi:[1,0,1] neg_lo:[1,0,0] neg_hi:[1,0,0]
	v_pk_add_f32 v[108:109], v[108:109], v[110:111]
	v_mul_f32_e32 v100, v107, v107
	v_pk_fma_f32 v[136:137], v[106:107], v[106:107], v[100:101] op_sel_hi:[1,1,0]
	v_pk_mul_f32 v[100:101], v[18:19], v[66:67] op_sel_hi:[1,0]
	v_pk_mul_f32 v[110:111], v[20:21], v[66:67] op_sel_hi:[1,0]
	v_pk_fma_f32 v[100:101], v[100:101], v[70:71], v[152:153] op_sel_hi:[1,0,1] neg_lo:[1,0,0] neg_hi:[1,0,0]
	v_pk_mul_f32 v[146:147], v[28:29], v[66:67] op_sel_hi:[1,0]
	v_pk_mul_f32 v[138:139], v[100:101], v[100:101]
	v_pk_mul_f32 v[142:143], v[24:25], v[66:67] op_sel_hi:[1,0]
	v_mov_b32_e32 v137, v138
	v_mov_b32_e32 v117, v139
	v_pk_add_f32 v[116:117], v[136:137], v[116:117]
	v_pk_fma_f32 v[122:123], v[146:147], v[70:71], v[122:123] op_sel_hi:[1,0,1] neg_lo:[1,0,0] neg_hi:[1,0,0]
	v_pk_add_f32 v[108:109], v[108:109], v[116:117]
	v_pk_fma_f32 v[116:117], v[110:111], v[70:71], v[154:155] op_sel_hi:[1,0,1] neg_lo:[1,0,0] neg_hi:[1,0,0]
	v_pk_add_f32 v[136:137], v[108:109], v[108:109] op_sel:[0,1] op_sel_hi:[1,0]
	v_pk_mul_f32 v[108:109], v[22:23], v[66:67] op_sel_hi:[1,0]
	v_mov_b32_e32 v138, v117
	v_pk_fma_f32 v[108:109], v[108:109], v[70:71], v[156:157] op_sel_hi:[1,0,1] neg_lo:[1,0,0] neg_hi:[1,0,0]
	v_mov_b32_e32 v110, v116
	v_mov_b32_e32 v139, v109
	v_mov_b32_e32 v111, v108
	v_pk_mul_f32 v[138:139], v[138:139], v[138:139]
	v_pk_fma_f32 v[118:119], v[142:143], v[70:71], v[118:119] op_sel_hi:[1,0,1] neg_lo:[1,0,0] neg_hi:[1,0,0]
	v_pk_fma_f32 v[110:111], v[110:111], v[110:111], v[138:139]
	v_pk_mul_f32 v[144:145], v[30:31], v[66:67] op_sel_hi:[1,0]
	v_pk_add_f32 v[138:139], v[110:111], v[110:111] op_sel:[0,1] op_sel_hi:[1,0]
	v_pk_mul_f32 v[110:111], v[26:27], v[66:67] op_sel_hi:[1,0]
	v_pk_mul_f32 v[146:147], v[122:123], v[122:123]
	v_pk_fma_f32 v[110:111], v[110:111], v[70:71], v[158:159] op_sel_hi:[1,0,1] neg_lo:[1,0,0] neg_hi:[1,0,0]
	v_mul_f32_e32 v142, v119, v119
	v_mul_f32_e32 v140, v111, v111
	v_pk_fma_f32 v[112:113], v[144:145], v[70:71], v[112:113] op_sel_hi:[1,0,1] neg_lo:[1,0,0] neg_hi:[1,0,0]
	v_mov_b32_e32 v137, v146
	v_mov_b32_e32 v139, v147
	v_pk_fma_f32 v[140:141], v[110:111], v[110:111], v[140:141] op_sel_hi:[1,1,0]
	v_pk_fma_f32 v[142:143], v[118:119], v[118:119], v[142:143] op_sel_hi:[1,1,0]
	v_pk_mul_f32 v[144:145], v[112:113], v[112:113]
	v_pk_add_f32 v[136:137], v[136:137], v[138:139]
	v_pk_mul_f32 v[138:139], v[2:3], v[66:67] op_sel_hi:[1,0]
	v_mov_b32_e32 v143, v144
	v_mov_b32_e32 v141, v145
	v_pk_fma_f32 v[124:125], v[138:139], v[70:71], v[124:125] op_sel_hi:[1,0,1] neg_lo:[1,0,0] neg_hi:[1,0,0]
	v_pk_mul_f32 v[138:139], v[0:1], v[66:67] op_sel_hi:[1,0]
	v_pk_add_f32 v[140:141], v[142:143], v[140:141]
	v_pk_fma_f32 v[132:133], v[138:139], v[70:71], v[132:133] op_sel_hi:[1,0,1] neg_lo:[1,0,0] neg_hi:[1,0,0]
	v_pk_mul_f32 v[144:145], v[10:11], v[66:67] op_sel_hi:[1,0]
	v_pk_mul_f32 v[146:147], v[8:9], v[66:67] op_sel_hi:[1,0]
	v_pk_add_f32 v[136:137], v[136:137], v[140:141]
	v_mov_b32_e32 v140, v133
	v_mov_b32_e32 v141, v125
	v_pk_fma_f32 v[130:131], v[144:145], v[70:71], v[130:131] op_sel_hi:[1,0,1] neg_lo:[1,0,0] neg_hi:[1,0,0]
	v_pk_fma_f32 v[120:121], v[146:147], v[70:71], v[120:121] op_sel_hi:[1,0,1] neg_lo:[1,0,0] neg_hi:[1,0,0]
	v_mov_b32_e32 v138, v132
	v_mov_b32_e32 v139, v124
	v_pk_mul_f32 v[140:141], v[140:141], v[140:141]
	v_mul_f32_e32 v144, v131, v131
	v_mul_f32_e32 v146, v121, v121
	v_pk_mul_f32 v[128:129], v[68:69], v[68:69]
	v_pk_fma_f32 v[138:139], v[138:139], v[138:139], v[140:141]
	v_pk_mul_f32 v[140:141], v[6:7], v[66:67] op_sel_hi:[1,0]
	v_pk_mul_f32 v[142:143], v[4:5], v[66:67] op_sel_hi:[1,0]
	v_pk_fma_f32 v[144:145], v[130:131], v[130:131], v[144:145] op_sel_hi:[1,1,0]
	v_pk_fma_f32 v[146:147], v[120:121], v[120:121], v[146:147] op_sel_hi:[1,1,0]
	v_pk_fma_f32 v[126:127], v[140:141], v[70:71], v[126:127] op_sel_hi:[1,0,1] neg_lo:[1,0,0] neg_hi:[1,0,0]
	v_pk_fma_f32 v[134:135], v[142:143], v[70:71], v[134:135] op_sel_hi:[1,0,1] neg_lo:[1,0,0] neg_hi:[1,0,0]
	v_mov_b32_e32 v147, v128
	v_mov_b32_e32 v145, v129
	v_mul_f32_e32 v140, v127, v127
	v_mul_f32_e32 v142, v135, v135
	v_pk_add_f32 v[128:129], v[146:147], v[144:145]
	v_pk_mul_f32 v[144:145], v[12:13], v[66:67] op_sel_hi:[1,0]
	v_pk_add_f32 v[136:137], v[136:137], v[136:137] op_sel:[0,1] op_sel_hi:[1,0]
	v_pk_add_f32 v[138:139], v[138:139], v[138:139] op_sel:[0,1] op_sel_hi:[1,0]
	v_pk_fma_f32 v[140:141], v[126:127], v[126:127], v[140:141] op_sel_hi:[1,1,0]
	v_pk_fma_f32 v[142:143], v[134:135], v[134:135], v[142:143] op_sel_hi:[1,1,0]
	v_pk_fma_f32 v[70:71], v[144:145], v[70:71], v[114:115] op_sel_hi:[1,0,1] neg_lo:[1,0,0] neg_hi:[1,0,0]
; __device__ __forceinline__ unsigned cvtpk(float lo, float hi) { f32x2_t v = {lo, hi}; bf16x2_t b = __builtin_convertvector(v, bf16x2_t); return __builtin_bit_cast(unsigned, b); }
; __device__ __forceinline__ float xhalf_sum(float m) { unsigned a = __builtin_bit_cast(unsigned, m), b = a; xswap(a, b); return __builtin_bit_cast(float, a) + __builtin_bit_cast(float, b); }
; __device__ __forceinline__ void attn_unit_a(FLAS unsigned char* lds, const Unit u) {
;     ...
;                 const float x0 = a0 - lam * (o[db][4 * g] * inv), x1 = a1 - lam * (o[db][4 * g + 1] * inv), x2 = a2 - lam * (o[db][4 * g + 2] * inv), x3 = a3 - lam * (o[db][4 * g + 3] * inv);
;                 o[db][4 * g] = x0; o[db][4 * g + 1] = x1; o[db][4 * g + 2] = x2; o[db][4 * g + 3] = x3; ss += (x0 * x0 + x1 * x1) + (x2 * x2 + x3 * x3); }
;         const float rr = 1.0f / sqrtf(xhalf_sum(ss) * (1.f / 128.f) + 1e-6f) * gsc;
; #pragma unroll
;         for (int db = 0; db < NDB; ++db)
; #pragma unroll
;             for (int g = 0; g < 4; ++g) { const float* gp = u.sgain + db * 32 + 8 * g + 4 * hi; u32x2 w;
;                 w.x = cvtpk(o[db][4 * g] * rr * gp[0], o[db][4 * g + 1] * rr * gp[1]); w.y = cvtpk(o[db][4 * g + 2] * rr * gp[2], o[db][4 * g + 3] * rr * gp[3]);
;                 *(u32x2*)(op + db * 32 + 8 * g) = w; }
	v_pk_add_f32 v[114:115], v[136:137], v[138:139]
	v_pk_mul_f32 v[136:137], v[70:71], v[70:71]
	v_pk_add_f32 v[138:139], v[142:143], v[140:141]
	v_mov_b32_e32 v115, v136
	v_mov_b32_e32 v139, v137
	v_pk_add_f32 v[114:115], v[114:115], v[138:139]
	s_nop 0
	v_pk_add_f32 v[114:115], v[114:115], v[128:129]
	s_nop 0
	v_pk_add_f32 v[114:115], v[114:115], v[114:115] op_sel:[0,1] op_sel_hi:[1,0]
	s_nop 0
	v_mov_b32_e32 v115, v114
	s_nop 1
	v_permlane32_swap_b32 v115, v114
	s_nop 1
	global_load_dwordx4 v[160:163], v67, s[8:9]
	global_load_dwordx4 v[164:167], v67, s[8:9] offset:32
	global_load_dwordx4 v[168:171], v67, s[8:9] offset:64
	global_load_dwordx4 v[172:175], v67, s[8:9] offset:96
	global_load_dwordx4 v[176:179], v67, s[8:9] offset:128
	global_load_dwordx4 v[180:183], v67, s[8:9] offset:160
	global_load_dwordx4 v[184:187], v67, s[8:9] offset:192
	global_load_dwordx4 v[200:203], v67, s[8:9] offset:224
	v_add_f32_e32 v114, v115, v114
	v_fmamk_f32 v114, v114, 0x3c000000, v240
	v_mul_f32_e32 v115, 0x4f800000, v114
	v_cmp_gt_f32_e32 vcc, s35, v114
	s_nop 1
	v_cndmask_b32_e32 v114, v114, v115, vcc
	v_sqrt_f32_e32 v115, v114
	s_nop 0
	v_add_u32_e32 v128, -1, v115
	v_fma_f32 v129, -v128, v115, v114
	v_cmp_ge_f32_e64 s[4:5], 0, v129
	v_add_u32_e32 v129, 1, v115
	s_nop 0
	v_cndmask_b32_e64 v128, v115, v128, s[4:5]
	v_fma_f32 v115, -v129, v115, v114
	v_cmp_lt_f32_e64 s[4:5], 0, v115
	s_nop 1
	v_cndmask_b32_e64 v115, v128, v129, s[4:5]
	v_mul_f32_e32 v128, 0x37800000, v115
	v_cndmask_b32_e32 v115, v115, v128, vcc
	v_cmp_class_f32_e32 vcc, v114, v244
	s_mov_b64 s[4:5], 0
	s_nop 0
	v_cndmask_b32_e32 v114, v115, v114, vcc
	v_div_scale_f32 v115, s[0:1], v114, v114, 1.0
	v_rcp_f32_e32 v128, v115
	s_nop 0
	v_fma_f32 v129, -v115, v128, 1.0
	v_fmac_f32_e32 v128, v129, v128
	v_div_scale_f32 v129, vcc, 1.0, v114, 1.0
	v_mul_f32_e32 v140, v129, v128
	v_fma_f32 v141, -v115, v140, v129
	v_fmac_f32_e32 v140, v141, v128
	v_fma_f32 v115, -v115, v140, v129
	v_div_fmas_f32 v115, v115, v128, v140
	v_div_fixup_f32 v114, v115, v114, 1.0
	v_mul_f32_e32 v114, v237, v114
	v_pk_mul_f32 v[78:79], v[78:79], v[114:115] op_sel_hi:[1,0]
	v_pk_mul_f32 v[72:73], v[72:73], v[114:115] op_sel_hi:[1,0]
	v_pk_mul_f32 v[74:75], v[74:75], v[114:115] op_sel_hi:[1,0]
	v_pk_mul_f32 v[76:77], v[76:77], v[114:115] op_sel_hi:[1,0]
	v_pk_mul_f32 v[70:71], v[70:71], v[114:115] op_sel_hi:[1,0]
	v_pk_mul_f32 v[68:69], v[68:69], v[114:115] op_sel_hi:[1,0]
	s_waitcnt vmcnt(7)
	v_pk_mul_f32 v[78:79], v[160:161], v[78:79]
	v_pk_mul_f32 v[72:73], v[162:163], v[72:73]
	v_cvt_pk_bf16_f32 v78, v78, v79
	v_cvt_pk_bf16_f32 v79, v72, v73
	global_store_dwordx2 v[64:65], v[78:79], off
	global_load_dwordx4 v[160:163], v67, s[8:9] offset:256
	v_pk_mul_f32 v[72:73], v[80:81], v[114:115] op_sel_hi:[1,0]
	v_pk_mul_f32 v[78:79], v[82:83], v[114:115] op_sel_hi:[1,0]
	s_waitcnt vmcnt(8)
	v_pk_mul_f32 v[72:73], v[164:165], v[72:73]
	v_pk_mul_f32 v[74:75], v[166:167], v[74:75]
	v_cvt_pk_bf16_f32 v72, v72, v73
	v_cvt_pk_bf16_f32 v73, v74, v75
	global_store_dwordx2 v[64:65], v[72:73], off offset:16
	global_load_dwordx4 v[164:167], v67, s[8:9] offset:288
	s_waitcnt vmcnt(9)
	v_pk_mul_f32 v[72:73], v[78:79], v[168:169]
	v_pk_mul_f32 v[74:75], v[76:77], v[170:171]
	v_cvt_pk_bf16_f32 v72, v72, v73
	v_cvt_pk_bf16_f32 v73, v74, v75
	global_store_dwordx2 v[64:65], v[72:73], off offset:32
	global_load_dwordx4 v[168:171], v67, s[8:9] offset:320
	v_pk_mul_f32 v[76:77], v[90:91], v[114:115] op_sel_hi:[1,0]
	v_pk_mul_f32 v[78:79], v[84:85], v[114:115] op_sel_hi:[1,0]
	s_waitcnt vmcnt(10)
	v_pk_mul_f32 v[72:73], v[76:77], v[172:173]
	v_pk_mul_f32 v[74:75], v[78:79], v[174:175]
	v_cvt_pk_bf16_f32 v72, v72, v73
	v_cvt_pk_bf16_f32 v73, v74, v75
	global_store_dwordx2 v[64:65], v[72:73], off offset:48
	global_load_dwordx4 v[172:175], v67, s[8:9] offset:352
	v_pk_mul_f32 v[76:77], v[92:93], v[114:115] op_sel_hi:[1,0]
	v_pk_mul_f32 v[78:79], v[86:87], v[114:115] op_sel_hi:[1,0]
	s_waitcnt vmcnt(11)
; __device__ __forceinline__ unsigned cvtpk(float lo, float hi) { f32x2_t v = {lo, hi}; bf16x2_t b = __builtin_convertvector(v, bf16x2_t); return __builtin_bit_cast(unsigned, b); }
; __device__ __forceinline__ void attn_unit_a(FLAS unsigned char* lds, const Unit u) {
;     ...
; #pragma unroll
;         for (int db = 0; db < NDB; ++db)
; #pragma unroll
;             for (int g = 0; g < 4; ++g) { const float* gp = u.sgain + db * 32 + 8 * g + 4 * hi; u32x2 w;
;                 w.x = cvtpk(o[db][4 * g] * rr * gp[0], o[db][4 * g + 1] * rr * gp[1]); w.y = cvtpk(o[db][4 * g + 2] * rr * gp[2], o[db][4 * g + 3] * rr * gp[3]);
;                 *(u32x2*)(op + db * 32 + 8 * g) = w; }
	v_pk_mul_f32 v[72:73], v[76:77], v[176:177]
	v_pk_mul_f32 v[74:75], v[78:79], v[178:179]
	v_cvt_pk_bf16_f32 v72, v72, v73
	v_cvt_pk_bf16_f32 v73, v74, v75
	global_store_dwordx2 v[64:65], v[72:73], off offset:64
	global_load_dwordx4 v[176:179], v67, s[8:9] offset:384
	v_pk_mul_f32 v[76:77], v[94:95], v[114:115] op_sel_hi:[1,0]
	v_pk_mul_f32 v[78:79], v[88:89], v[114:115] op_sel_hi:[1,0]
	s_waitcnt vmcnt(12)
	v_pk_mul_f32 v[72:73], v[76:77], v[180:181]
	v_pk_mul_f32 v[74:75], v[78:79], v[182:183]
	v_cvt_pk_bf16_f32 v72, v72, v73
	v_cvt_pk_bf16_f32 v73, v74, v75
	global_store_dwordx2 v[64:65], v[72:73], off offset:80
	global_load_dwordx4 v[180:183], v67, s[8:9] offset:416
	v_pk_mul_f32 v[76:77], v[102:103], v[114:115] op_sel_hi:[1,0]
	v_pk_mul_f32 v[78:79], v[96:97], v[114:115] op_sel_hi:[1,0]
	s_waitcnt vmcnt(13)
	v_pk_mul_f32 v[72:73], v[76:77], v[184:185]
	v_pk_mul_f32 v[74:75], v[78:79], v[186:187]
	v_cvt_pk_bf16_f32 v72, v72, v73
	v_cvt_pk_bf16_f32 v73, v74, v75
	global_store_dwordx2 v[64:65], v[72:73], off offset:96
	global_load_dwordx4 v[184:187], v67, s[8:9] offset:448
	v_pk_mul_f32 v[76:77], v[106:107], v[114:115] op_sel_hi:[1,0]
	v_pk_mul_f32 v[78:79], v[98:99], v[114:115] op_sel_hi:[1,0]
	s_waitcnt vmcnt(14)
	v_pk_mul_f32 v[72:73], v[76:77], v[200:201]
	v_pk_mul_f32 v[74:75], v[78:79], v[202:203]
	v_cvt_pk_bf16_f32 v72, v72, v73
	v_cvt_pk_bf16_f32 v73, v74, v75
	global_store_dwordx2 v[64:65], v[72:73], off offset:112
	global_load_dwordx4 v[200:203], v67, s[8:9] offset:480
	v_pk_mul_f32 v[76:77], v[104:105], v[114:115] op_sel_hi:[1,0]
	v_pk_mul_f32 v[78:79], v[100:101], v[114:115] op_sel_hi:[1,0]
	s_waitcnt vmcnt(14)
	v_pk_mul_f32 v[72:73], v[76:77], v[160:161]
	v_pk_mul_f32 v[74:75], v[78:79], v[162:163]
	v_cvt_pk_bf16_f32 v72, v72, v73
	v_cvt_pk_bf16_f32 v73, v74, v75
	global_store_dwordx2 v[64:65], v[72:73], off offset:128
	v_pk_mul_f32 v[76:77], v[116:117], v[114:115] op_sel_hi:[1,0]
	v_pk_mul_f32 v[78:79], v[108:109], v[114:115] op_sel_hi:[1,0]
	s_waitcnt vmcnt(13)
	v_pk_mul_f32 v[72:73], v[76:77], v[164:165]
	v_pk_mul_f32 v[74:75], v[78:79], v[166:167]
	v_cvt_pk_bf16_f32 v72, v72, v73
	v_cvt_pk_bf16_f32 v73, v74, v75
	global_store_dwordx2 v[64:65], v[72:73], off offset:144
	v_pk_mul_f32 v[76:77], v[118:119], v[114:115] op_sel_hi:[1,0]
	v_pk_mul_f32 v[78:79], v[110:111], v[114:115] op_sel_hi:[1,0]
	s_waitcnt vmcnt(12)
	v_pk_mul_f32 v[72:73], v[76:77], v[168:169]
	v_pk_mul_f32 v[74:75], v[78:79], v[170:171]
	v_cvt_pk_bf16_f32 v72, v72, v73
	v_cvt_pk_bf16_f32 v73, v74, v75
	global_store_dwordx2 v[64:65], v[72:73], off offset:160
	v_pk_mul_f32 v[76:77], v[122:123], v[114:115] op_sel_hi:[1,0]
	v_pk_mul_f32 v[78:79], v[112:113], v[114:115] op_sel_hi:[1,0]
	s_waitcnt vmcnt(11)
	v_pk_mul_f32 v[72:73], v[76:77], v[172:173]
	v_pk_mul_f32 v[74:75], v[78:79], v[174:175]
	v_cvt_pk_bf16_f32 v72, v72, v73
	v_cvt_pk_bf16_f32 v73, v74, v75
	global_store_dwordx2 v[64:65], v[72:73], off offset:176
	v_pk_mul_f32 v[76:77], v[132:133], v[114:115] op_sel_hi:[1,0]
	v_pk_mul_f32 v[78:79], v[124:125], v[114:115] op_sel_hi:[1,0]
	s_waitcnt vmcnt(10)
	v_pk_mul_f32 v[72:73], v[76:77], v[176:177]
	v_pk_mul_f32 v[74:75], v[78:79], v[178:179]
	v_cvt_pk_bf16_f32 v72, v72, v73
	v_cvt_pk_bf16_f32 v73, v74, v75
	global_store_dwordx2 v[64:65], v[72:73], off offset:192
	v_pk_mul_f32 v[76:77], v[134:135], v[114:115] op_sel_hi:[1,0]
	v_pk_mul_f32 v[78:79], v[126:127], v[114:115] op_sel_hi:[1,0]
	s_waitcnt vmcnt(9)
	v_pk_mul_f32 v[72:73], v[76:77], v[180:181]
	v_pk_mul_f32 v[74:75], v[78:79], v[182:183]
	v_cvt_pk_bf16_f32 v72, v72, v73
	v_cvt_pk_bf16_f32 v73, v74, v75
	global_store_dwordx2 v[64:65], v[72:73], off offset:208
	v_pk_mul_f32 v[76:77], v[120:121], v[114:115] op_sel_hi:[1,0]
	v_pk_mul_f32 v[78:79], v[130:131], v[114:115] op_sel_hi:[1,0]
	s_waitcnt vmcnt(8)
	v_pk_mul_f32 v[72:73], v[76:77], v[184:185]
	v_pk_mul_f32 v[74:75], v[78:79], v[186:187]
	v_cvt_pk_bf16_f32 v72, v72, v73
	v_cvt_pk_bf16_f32 v73, v74, v75
	global_store_dwordx2 v[64:65], v[72:73], off offset:224
	s_waitcnt vmcnt(7)
	v_pk_mul_f32 v[72:73], v[70:71], v[200:201]
	v_pk_mul_f32 v[70:71], v[68:69], v[202:203]
	v_cvt_pk_bf16_f32 v68, v72, v73
